# unit queues: ticket atomic issued before the loop-top barrier so its latency overlaps the wait for the other waves
# speedup vs baseline: 1.0042x; 1.0042x over previous
; DI void unpack8(uint4 v, float* f) { f[0] = bflo(v.x); f[1] = bfhi(v.x); f[2] = bflo(v.y); f[3] = bfhi(v.y); f[4] = bflo(v.z); f[5] = bfhi(v.z); f[6] = bflo(v.w); f[7] = bfhi(v.w); }
; DI float ex2(float x) { return __builtin_amdgcn_exp2f(x); }
; DI void norm_unit(const Params& p, int layer, int half, int nu, int tid) { norm_rows(p, layer, half * HROWS + nu * 64, 64, 0, 8, tid); }
; #define otid() otid_(wbase)
; DI void ret_local_unit(const Params& p, int hf, int bl, int c, int hd, unsigned char* shm, int tid) {
;     ...
;   const float lg = logf(1.0f - ex2(-5.0f - (float)hd));
; #pragma unroll
;   for (int it = 0; it < 2; ++it) {
;     const int idx = tid + it * NTHR, j = idx >> 3, dg = idx & 7;
;     const bf16_t* base = projb + (size_t)(c * 128 + j) * NP;
;     float k1[8], k2[8]; unpack8(*(const uint4*)(base + C_RK + hd * 128 + dg * 8), k1); unpack8(*(const uint4*)(base + C_RK + hd * 128 + 64 + dg * 8), k2);
;     const float w = __expf(lg * (float)(127 - j)) * 0.08838834764831845f;
; __global__ void __launch_bounds__(NTHR) mega(Params p) {
;     ...
;         int* my = ctr + 8 + phase_id;
;         for (;;) {
;           __syncthreads();
;           if (otid() == 0) s_unit = atomicAdd(my, 1);
;           __syncthreads();
;           const int u0 = s_unit;
;           const int n_fill = (hf == 0 && layer > 0) ? 256 : 0;
;           int u = u0;
;           if (u >= 784 + n_fill) break;
;           if (u >= 16 && u < 16 + n_fill) { norm_unit(p, layer, 1, u - 16, otid()); continue; }
;           if (u >= 16) u -= n_fill;
;           if (u < 16) fox_cumsum_unit(p, hf, u >> 3, u & 7, shm, otid());
;           else if (u < 272) { const int k = u - 16; ssd_local_unit(p, layer, hf, k >> 7, (k >> 1) & 63, k & 1, shm, otid()); }
;           else { const int k = u - 272; ret_local_unit(p, hf, k >> 8, (k >> 2) & 63, k & 3, shm, otid()); }
.LBB0_237:
	v_mov_b32_e32 v0, v163
	s_nop 0
	v_cmp_eq_u32_e32 vcc, 0, v0
	s_and_saveexec_b64 s[0:1], vcc
	s_cbranch_execz .Lp2c_nb
	s_mov_b64 s[6:7], exec
	v_mbcnt_lo_u32_b32 v0, s6, 0
	v_mbcnt_hi_u32_b32 v0, s7, v0
	v_cmp_eq_u32_e32 vcc, 0, v0
	s_and_saveexec_b64 s[4:5], vcc
	s_cbranch_execz .LBB0_240
	s_bcnt1_i32_b64 s2, s[6:7]
	v_mov_b32_e32 v1, s2
	global_atomic_add v1, v161, v1, s[16:17] sc0
.LBB0_240:
	s_or_b64 exec, exec, s[4:5]
	s_barrier
	s_waitcnt vmcnt(0)
	v_readfirstlane_b32 s2, v1
	s_nop 1
	v_add_u32_e32 v0, s2, v0
	ds_write_b32 v161, v0 offset:16
	s_branch .LBB0_241
.Lp2c_nb:
	s_barrier
.LBB0_241:
	s_or_b64 exec, exec, s[0:1]
	s_waitcnt lgkmcnt(0)
	s_barrier
	ds_read_b32 v0, v161 offset:16
	s_mov_b64 s[0:1], -1
	s_waitcnt lgkmcnt(0)
	v_cmp_le_i32_e32 vcc, s56, v0
	v_readfirstlane_b32 s58, v0
	s_cbranch_vccnz .LBB0_236
	s_cmp_gt_i32 s58, 15
	s_cselect_b64 s[0:1], -1, 0
	s_cmp_lt_i32 s58, s57
	s_cselect_b64 s[4:5], -1, 0
	s_and_b64 s[4:5], s[0:1], s[4:5]
	s_andn2_b64 vcc, exec, s[4:5]
	s_mov_b64 s[4:5], -1
	s_cbranch_vccz .LBB0_353
	s_and_b64 s[0:1], s[0:1], exec
	s_cselect_b32 s0, s13, 0
	s_sub_i32 s24, s58, s0
	s_cmp_gt_i32 s24, 15
	s_mov_b64 s[0:1], -1
	s_cbranch_scc0 .LBB0_312
	s_cmpk_gt_u32 s24, 0x10f
	s_cbranch_scc0 .LBB0_246
	s_cmpk_gt_u32 s24, 0x30f
	s_cbranch_scc1 .Lkmx_unit
	s_add_i32 s8, s24, 0xfffffef0
	s_lshr_b32 s4, s8, 8
	s_mul_i32 s2, s4, 0x3400000
	s_bfe_u32 s10, s8, 0x60002
	s_and_b32 s9, s58, 3
	s_lshl_b64 s[0:1], s[2:3], 1
	s_add_u32 s6, s38, s0
	s_addc_u32 s7, s39, s1
	s_lshl_b32 s0, s4, 13
	v_cvt_f32_ubyte0_e32 v0, s9
	s_add_i32 s0, s0, s68
	s_lshl_b32 s11, s10, 7
	v_sub_f32_e32 v0, 0xc0a00000, v0
	s_or_b32 s0, s0, s11
	v_exp_f32_e32 v0, v0
	s_lshl_b32 s2, s0, 6
	s_lshl_b64 s[0:1], s[2:3], 3
	v_readlane_b32 s2, v252, 45
	s_add_u32 s4, s2, s0
	v_readlane_b32 s0, v252, 46
	s_addc_u32 s5, s0, s1
	v_sub_f32_e32 v0, 1.0, v0
	s_mov_b32 s0, 0x800000
	v_cmp_gt_f32_e32 vcc, s0, v0
	s_and_b64 s[0:1], vcc, exec
	s_cselect_b32 s0, 32, 0
	v_ldexp_f32 v0, v0, s0
	v_log_f32_e32 v0, v0
	s_mov_b32 s0, 0x3f317217
	v_mov_b32_e32 v18, v163
	v_mul_f32_e32 v1, 0x3f317217, v0
	v_fma_f32 v1, v0, s0, -v1
	v_fmac_f32_e32 v1, 0x3377d1cf, v0
	s_mov_b32 s0, 0x7f800000
	v_fmac_f32_e32 v1, 0x3f317217, v0
	v_cmp_lt_f32_e64 s[0:1], |v0|, s0
	v_ashrrev_i32_e32 v13, 3, v18
	v_mov_b64_e32 v[14:15], s[6:7]
	v_cndmask_b32_e64 v0, v0, v1, s[0:1]
	v_cndmask_b32_e32 v1, 0, v201, vcc
	v_sub_f32_e32 v21, v0, v1
	v_and_b32_e32 v0, 7, v18
	v_lshlrev_b32_e32 v20, 3, v0
	v_lshlrev_b32_e32 v160, 4, v0
	v_lshlrev_b32_e32 v12, 5, v0
	v_add_u32_e32 v0, s11, v13
	v_mad_i64_i32 v[0:1], s[0:1], v0, s65, v[14:15]
	s_lshl_b32 s2, s9, 8
	v_lshl_add_u64 v[16:17], v[0:1], 0, s[2:3]
	v_lshl_add_u64 v[4:5], v[16:17], 0, v[160:161]
	v_lshl_add_u64 v[208:209], v[16:17], 0, v[160:161]
	global_load_dwordx4 v[100:103], v[208:209], off offset:1024
	global_load_dwordx4 v[104:107], v[208:209], off offset:1152
	v_lshl_or_b32 v210, v13, 6, v20
	v_mov_b32_e32 v211, v161
	v_lshl_add_u64 v[210:211], v[210:211], 3, s[4:5]
	global_load_dwordx4 v[108:111], v[210:211], off offset:48
	global_load_dwordx4 v[112:115], v[210:211], off offset:32
	global_load_dwordx4 v[116:119], v[210:211], off offset:16
	global_load_dwordx4 v[120:123], v[210:211], off
	v_mov_b32_e32 v212, v12
	v_mov_b32_e32 v213, v161
	v_lshl_add_u64 v[212:213], v[16:17], 0, v[212:213]
	global_load_dwordx4 v[124:127], v[212:213], off offset:2048
	global_load_dwordx4 v[128:131], v[212:213], off offset:2064
	v_add_u32_e32 v222, 64, v13
	v_add_u32_e32 v223, s11, v222
	v_mad_i64_i32 v[214:215], s[0:1], v223, s65, v[14:15]
	v_lshl_add_u64 v[214:215], v[214:215], 0, s[2:3]
	v_lshl_add_u64 v[216:217], v[214:215], 0, v[160:161]
	global_load_dwordx4 v[132:135], v[216:217], off offset:1024
	global_load_dwordx4 v[136:139], v[216:217], off offset:1152
	v_lshl_or_b32 v218, v222, 6, v20
	v_mov_b32_e32 v219, v161
	v_lshl_add_u64 v[218:219], v[218:219], 3, s[4:5]
	global_load_dwordx4 v[140:143], v[218:219], off offset:48
	global_load_dwordx4 v[144:147], v[218:219], off offset:32
	global_load_dwordx4 v[148:151], v[218:219], off offset:16
	global_load_dwordx4 v[152:155], v[218:219], off
	v_mov_b32_e32 v220, v12
	v_mov_b32_e32 v221, v161
	v_lshl_add_u64 v[220:221], v[214:215], 0, v[220:221]
	global_load_dwordx4 v[156:159], v[220:221], off offset:2048
	global_load_dwordx4 v[204:207], v[220:221], off offset:2064
	v_add_u32_e32 v19, 32, v12
	s_waitcnt vmcnt(15)
	v_mov_b32_e32 v0, v100
	v_mov_b32_e32 v1, v101
	v_mov_b32_e32 v2, v102
	v_mov_b32_e32 v3, v103
	v_lshlrev_b32_e32 v26, 16, v0
	v_and_b32_e32 v27, 0xffff0000, v0
	v_lshlrev_b32_e32 v28, 16, v1
	v_and_b32_e32 v29, 0xffff0000, v1
	v_lshlrev_b32_e32 v30, 16, v2
	v_and_b32_e32 v31, 0xffff0000, v2
	v_lshlrev_b32_e32 v32, 16, v3
	v_and_b32_e32 v33, 0xffff0000, v3
	s_waitcnt vmcnt(14)
	v_mov_b32_e32 v0, v104
	v_mov_b32_e32 v1, v105
	v_mov_b32_e32 v2, v106
	v_mov_b32_e32 v3, v107
	v_lshlrev_b32_e32 v34, 16, v0
	v_and_b32_e32 v35, 0xffff0000, v0
	v_sub_u32_e32 v0, 0x7f, v13
	v_cvt_f32_i32_e32 v0, v0
	v_lshlrev_b32_e32 v36, 16, v1
	v_and_b32_e32 v37, 0xffff0000, v1
	v_lshlrev_b32_e32 v38, 16, v2
	v_mul_f32_e32 v0, v21, v0
	v_mul_f32_e32 v0, 0x3fb8aa3b, v0
	v_exp_f32_e32 v0, v0
	v_and_b32_e32 v39, 0xffff0000, v2
	v_lshlrev_b32_e32 v40, 16, v3
	v_and_b32_e32 v41, 0xffff0000, v3
	v_mul_f32_e32 v42, 0x3db504f3, v0
	v_lshl_or_b32 v0, v13, 6, v20
	v_ashrrev_i32_e32 v1, 31, v0
	v_lshl_add_u64 v[22:23], v[0:1], 3, s[4:5]
	s_nop 0
	s_waitcnt vmcnt(10)
; DI void unpack8(uint4 v, float* f) { f[0] = bflo(v.x); f[1] = bfhi(v.x); f[2] = bflo(v.y); f[3] = bfhi(v.y); f[4] = bflo(v.z); f[5] = bfhi(v.z); f[6] = bflo(v.w); f[7] = bfhi(v.w); }
; DI uint4 pack8(const float* f) { uint4 r; r.x = pk2(f[0], f[1]); r.y = pk2(f[2], f[3]); r.z = pk2(f[4], f[5]); r.w = pk2(f[6], f[7]); return r; }
; DI void ret_local_unit(const Params& p, int hf, int bl, int c, int hd, unsigned char* shm, int tid) {
;     ...
;   for (int it = 0; it < 2; ++it) {
;     const int idx = tid + it * NTHR, j = idx >> 3, dg = idx & 7;
;     const bf16_t* base = projb + (size_t)(c * 128 + j) * NP;
;     float k1[8], k2[8]; unpack8(*(const uint4*)(base + C_RK + hd * 128 + dg * 8), k1); unpack8(*(const uint4*)(base + C_RK + hd * 128 + 64 + dg * 8), k2);
;     const float w = __expf(lg * (float)(127 - j)) * 0.08838834764831845f;
;     float o1[8], o2[8];
; #pragma unroll
;     for (int e = 0; e < 8; ++e) {
;       const float2 t = cs[j * 64 + dg * 8 + e];
;       o1[e] = (k1[e] * t.x - k2[e] * t.y) * w; o2[e] = (k1[e] * t.y + k2[e] * t.x) * w;
;     }
;     *(uint4*)(sK + j * LD + dg * 8) = pack8(o1); *(uint4*)(sK + j * LD + 64 + dg * 8) = pack8(o2);
;     *(uint4*)(sV + j * LD + dg * 16) = *(const uint4*)(base + C_RV + hd * 128 + dg * 16);
;     *(uint4*)(sV + j * LD + dg * 16 + 8) = *(const uint4*)(base + C_RV + hd * 128 + dg * 16 + 8);
;   }
;   __syncthreads();
	v_mov_b32_e32 v0, v108
	v_mov_b32_e32 v1, v109
	v_mov_b32_e32 v2, v110
	v_mov_b32_e32 v3, v111
	v_mov_b32_e32 v4, v112
	v_mov_b32_e32 v5, v113
	v_mov_b32_e32 v6, v114
	v_mov_b32_e32 v7, v115
	v_mov_b32_e32 v8, v116
	v_mov_b32_e32 v9, v117
	v_mov_b32_e32 v10, v118
	v_mov_b32_e32 v11, v119
	v_mov_b32_e32 v22, v120
	v_mov_b32_e32 v23, v121
	v_mov_b32_e32 v24, v122
	v_mov_b32_e32 v25, v123
	v_mul_f32_e32 v43, v23, v34
	v_mul_f32_e32 v23, v23, v26
	v_fmac_f32_e32 v23, v22, v34
	v_fma_f32 v43, v22, v26, -v43
	v_mul_f32_e32 v22, v42, v23
	v_mul_f32_e32 v23, v25, v35
	v_mul_f32_e32 v25, v25, v27
	v_fmac_f32_e32 v25, v24, v35
	v_fma_f32 v23, v24, v27, -v23
	v_mul_f32_e32 v24, v42, v25
	v_mul_f32_e32 v25, v9, v36
	v_mul_f32_e32 v9, v9, v28
	v_fmac_f32_e32 v9, v8, v36
	v_fma_f32 v25, v8, v28, -v25
	v_mul_f32_e32 v8, v42, v9
	v_mul_f32_e32 v9, v11, v37
	v_mul_f32_e32 v11, v11, v29
	v_fmac_f32_e32 v11, v10, v37
	v_fma_f32 v9, v10, v29, -v9
	v_mul_f32_e32 v10, v42, v11
	v_mul_f32_e32 v11, v5, v38
	v_mul_f32_e32 v5, v5, v30
	v_fmac_f32_e32 v5, v4, v38
	v_fma_f32 v11, v4, v30, -v11
	v_mul_f32_e32 v4, v42, v5
	v_mul_f32_e32 v5, v7, v39
	v_mul_f32_e32 v7, v7, v31
	v_fmac_f32_e32 v7, v6, v39
	v_fma_f32 v5, v6, v31, -v5
	v_mul_f32_e32 v6, v42, v7
	v_mul_f32_e32 v7, v1, v40
	v_mul_f32_e32 v1, v1, v32
	v_fma_f32 v7, v0, v32, -v7
	v_fmac_f32_e32 v1, v0, v40
	v_mul_f32_e32 v0, v3, v41
	v_fma_f32 v0, v2, v33, -v0
	v_mul_f32_e32 v27, v42, v0
	v_mul_f32_e32 v0, v3, v33
	v_mul_f32_e32 v7, v42, v7
	v_fmac_f32_e32 v0, v2, v41
	v_mul_f32_e32 v43, v42, v43
	v_mul_f32_e32 v23, v42, v23
	v_mul_f32_e32 v25, v42, v25
	v_mul_f32_e32 v9, v42, v9
	v_mul_f32_e32 v11, v42, v11
	v_mul_f32_e32 v5, v42, v5
	v_mul_f32_e32 v26, v42, v1
	v_mul_f32_e32 v28, v42, v0
	v_cvt_pk_bf16_f32 v0, v43, v23
	v_cvt_pk_bf16_f32 v1, v25, v9
	v_cvt_pk_bf16_f32 v2, v11, v5
	v_cvt_pk_bf16_f32 v3, v7, v27
	v_mul_lo_u32 v7, v13, s66
	v_add3_u32 v5, 32, v7, v160
	v_mov_b32_e32 v13, v161
	ds_write_b128 v5, v[0:3]
	v_cvt_pk_bf16_f32 v0, v22, v24
	v_cvt_pk_bf16_f32 v1, v8, v10
	v_cvt_pk_bf16_f32 v2, v4, v6
	v_cvt_pk_bf16_f32 v3, v26, v28
	ds_write_b128 v5, v[0:3] offset:128
	v_lshl_add_u64 v[4:5], v[16:17], 0, v[12:13]
	v_add_u32_e32 v6, v19, v7
	s_waitcnt vmcnt(9)
	v_mov_b32_e32 v0, v124
	v_mov_b32_e32 v1, v125
	v_mov_b32_e32 v2, v126
	v_mov_b32_e32 v3, v127
	ds_write_b128 v6, v[0:3] offset:34816
	s_waitcnt vmcnt(8)
	v_mov_b32_e32 v0, v128
	v_mov_b32_e32 v1, v129
	v_mov_b32_e32 v2, v130
	v_mov_b32_e32 v3, v131
	ds_write_b128 v6, v[0:3] offset:34832
	v_add_u32_e32 v0, 0x200, v18
	v_ashrrev_i32_e32 v24, 3, v0
	v_add_u32_e32 v0, s11, v24
	v_mad_i64_i32 v[0:1], s[0:1], v0, s65, v[14:15]
	v_lshl_add_u64 v[0:1], v[0:1], 0, s[2:3]
	v_lshl_add_u64 v[6:7], v[0:1], 0, v[160:161]
	s_and_b32 s0, s8, 0x3ff00
	s_lshl_b32 s1, s10, 2
	s_or_b32 s0, s1, s0
	s_or_b32 s0, s0, s9
	s_lshl_b32 s2, s0, 14
	s_lshl_b64 s[0:1], s[2:3], 1
	v_readlane_b32 s2, v253, 28
	s_add_u32 s0, s2, s0
	v_readlane_b32 s2, v253, 29
	s_addc_u32 s1, s2, s1
	s_waitcnt vmcnt(7)
	v_mov_b32_e32 v2, v132
	v_mov_b32_e32 v3, v133
	v_mov_b32_e32 v4, v134
	v_mov_b32_e32 v5, v135
	v_lshlrev_b32_e32 v25, 16, v2
	v_and_b32_e32 v26, 0xffff0000, v2
	v_lshlrev_b32_e32 v27, 16, v3
	v_and_b32_e32 v28, 0xffff0000, v3
	v_lshlrev_b32_e32 v29, 16, v4
	v_and_b32_e32 v30, 0xffff0000, v4
	v_lshlrev_b32_e32 v31, 16, v5
	v_and_b32_e32 v32, 0xffff0000, v5
	s_waitcnt vmcnt(6)
	v_mov_b32_e32 v2, v136
	v_mov_b32_e32 v3, v137
	v_mov_b32_e32 v4, v138
	v_mov_b32_e32 v5, v139
	v_lshlrev_b32_e32 v33, 16, v2
	v_and_b32_e32 v34, 0xffff0000, v2
	v_sub_u32_e32 v2, 0x7f, v24
	v_cvt_f32_i32_e32 v2, v2
	v_lshlrev_b32_e32 v35, 16, v3
	v_and_b32_e32 v36, 0xffff0000, v3
	v_lshlrev_b32_e32 v37, 16, v4
	v_mul_f32_e32 v2, v21, v2
	v_mul_f32_e32 v2, 0x3fb8aa3b, v2
	v_exp_f32_e32 v2, v2
	v_and_b32_e32 v38, 0xffff0000, v4
	v_lshlrev_b32_e32 v39, 16, v5
	v_and_b32_e32 v40, 0xffff0000, v5
	v_mul_f32_e32 v41, 0x3db504f3, v2
	v_lshl_or_b32 v2, v24, 6, v20
	v_ashrrev_i32_e32 v3, 31, v2
	v_lshl_add_u64 v[10:11], v[2:3], 3, s[4:5]
	s_waitcnt vmcnt(2)
	v_mov_b32_e32 v2, v140
	v_mov_b32_e32 v3, v141
	v_mov_b32_e32 v4, v142
	v_mov_b32_e32 v5, v143
	v_mov_b32_e32 v6, v144
	v_mov_b32_e32 v7, v145
	v_mov_b32_e32 v8, v146
	v_mov_b32_e32 v9, v147
	v_mov_b32_e32 v14, v148
	v_mov_b32_e32 v15, v149
	v_mov_b32_e32 v16, v150
	v_mov_b32_e32 v17, v151
	v_mov_b32_e32 v20, v152
	v_mov_b32_e32 v21, v153
	v_mov_b32_e32 v22, v154
	v_mov_b32_e32 v23, v155
	v_mul_f32_e32 v10, v21, v33
	v_mul_f32_e32 v11, v21, v25
	v_fma_f32 v10, v20, v25, -v10
	v_fmac_f32_e32 v11, v20, v33
	v_mul_f32_e32 v20, v23, v34
	v_mul_f32_e32 v21, v23, v26
	v_fma_f32 v20, v22, v26, -v20
	v_fmac_f32_e32 v21, v22, v34
	v_mul_f32_e32 v22, v15, v35
	v_mul_f32_e32 v15, v15, v27
	v_fmac_f32_e32 v15, v14, v35
	v_fma_f32 v22, v14, v27, -v22
	v_mul_f32_e32 v14, v41, v15
	v_mul_f32_e32 v15, v17, v36
	v_mul_f32_e32 v17, v17, v28
	v_fmac_f32_e32 v17, v16, v36
	v_fma_f32 v15, v16, v28, -v15
	v_mul_f32_e32 v16, v41, v17
	v_mul_f32_e32 v17, v7, v37
	v_mul_f32_e32 v7, v7, v29
	v_fmac_f32_e32 v7, v6, v37
	v_fma_f32 v17, v6, v29, -v17
	v_mul_f32_e32 v6, v41, v7
	v_mul_f32_e32 v7, v9, v38
	v_mul_f32_e32 v9, v9, v30
	v_fmac_f32_e32 v9, v8, v38
	v_fma_f32 v7, v8, v30, -v7
	v_mul_f32_e32 v8, v41, v9
	v_mul_f32_e32 v9, v3, v39
	v_mul_f32_e32 v3, v3, v31
	v_fma_f32 v9, v2, v31, -v9
	v_fmac_f32_e32 v3, v2, v39
	v_mul_f32_e32 v2, v5, v40
	v_fma_f32 v2, v4, v32, -v2
	v_mul_f32_e32 v25, v41, v2
	v_mul_f32_e32 v2, v5, v32
	v_mul_f32_e32 v7, v41, v7
	v_fmac_f32_e32 v2, v4, v40
	v_mul_f32_e32 v10, v41, v10
	v_mul_f32_e32 v20, v41, v20
	v_mul_f32_e32 v22, v41, v22
	v_mul_f32_e32 v15, v41, v15
	v_mul_f32_e32 v17, v41, v17
	v_mul_f32_e32 v9, v41, v9
	v_mul_f32_e32 v23, v41, v3
	v_mul_f32_e32 v26, v41, v2
	v_cvt_pk_bf16_f32 v2, v10, v20
	v_cvt_pk_bf16_f32 v3, v22, v15
	v_cvt_pk_bf16_f32 v4, v17, v7
	v_mul_lo_u32 v7, v24, s66
	v_cvt_pk_bf16_f32 v5, v9, v25
	v_add3_u32 v9, 32, v7, v160
	v_mul_f32_e32 v11, v41, v11
	v_mul_f32_e32 v21, v41, v21
	ds_write_b128 v9, v[2:5]
	v_cvt_pk_bf16_f32 v2, v11, v21
	v_cvt_pk_bf16_f32 v3, v14, v16
	v_cvt_pk_bf16_f32 v4, v6, v8
	v_cvt_pk_bf16_f32 v5, v23, v26
	ds_write_b128 v9, v[2:5] offset:128
	v_lshl_add_u64 v[4:5], v[0:1], 0, v[12:13]
	v_add_u32_e32 v6, v19, v7
	s_waitcnt vmcnt(1)
	v_mov_b32_e32 v0, v156
	v_mov_b32_e32 v1, v157
	v_mov_b32_e32 v2, v158
	v_mov_b32_e32 v3, v159
	ds_write_b128 v6, v[0:3] offset:34816
	v_ashrrev_i32_e32 v4, 6, v18
	v_and_b32_e32 v5, 15, v18
	v_lshlrev_b32_e32 v5, 7, v5
	s_waitcnt vmcnt(0)
	v_mov_b32_e32 v0, v204
	v_mov_b32_e32 v1, v205
	v_mov_b32_e32 v2, v206
	v_mov_b32_e32 v3, v207
	ds_write_b128 v6, v[0:3] offset:34832
	v_lshrrev_b32_e32 v0, 1, v18
	v_and_b32_e32 v160, 24, v0
	v_bfe_u32 v0, v18, 2, 2
	v_or_b32_e32 v0, v160, v0
	v_lshlrev_b32_e32 v1, 3, v18
	v_mul_u32_u24_e32 v0, 0x88, v0
	v_and_b32_e32 v1, 24, v1
	v_lshlrev_b32_e32 v0, 1, v0
	v_add3_u32 v6, 32, v1, v0
	v_lshl_add_u32 v7, v4, 5, v6
	s_waitcnt lgkmcnt(0)
	s_barrier
; DI f32x4 mmaT(bf16x8 a_m, bf16x8 b_n, f32x4 c) { return __builtin_amdgcn_mfma_f32_16x16x32_bf16(b_n, a_m, c, 0, 0, 0); }
; DI void ret_local_unit(const Params& p, int hf, int bl, int c, int hd, unsigned char* shm, int tid) {
;     ...
;   const int wid = tid >> 6, lane = tid & 63, fr = lane & 15, fq = lane >> 4;
;   f32x4 acc[8];
; #pragma unroll
;   for (int n = 0; n < 8; ++n) acc[n] = (f32x4){0.f, 0.f, 0.f, 0.f};
; #pragma unroll
;   for (int ks = 0; ks < 4; ++ks) {
;     const bf16x8 a = frag_tr(sV, LD, 32 * ks, 16 * wid, fr, fq);
; #pragma unroll
;     for (int n = 0; n < 8; ++n) acc[n] = mmaT(a, frag_tr(sK, LD, 32 * ks, 16 * n, fr, fq), acc[n]);
;   }
	ds_read_b64_tr_b16 v[0:1], v7 offset:34816
	ds_read_b64_tr_b16 v[2:3], v7 offset:35904
	ds_read_b64_tr_b16 v[10:11], v6 offset:1088
	ds_read_b64_tr_b16 v[8:9], v6
	ds_read_b64_tr_b16 v[12:13], v6 offset:32
	ds_read_b64_tr_b16 v[14:15], v6 offset:1120
	ds_read_b64_tr_b16 v[16:17], v6 offset:64
	ds_read_b64_tr_b16 v[18:19], v6 offset:1152
	ds_read_b64_tr_b16 v[20:21], v6 offset:96
	ds_read_b64_tr_b16 v[22:23], v6 offset:1184
	ds_read_b64_tr_b16 v[24:25], v6 offset:128
	ds_read_b64_tr_b16 v[26:27], v6 offset:1216
	ds_read_b64_tr_b16 v[28:29], v6 offset:160
	ds_read_b64_tr_b16 v[30:31], v6 offset:1248
	ds_read_b64_tr_b16 v[32:33], v6 offset:192
	ds_read_b64_tr_b16 v[34:35], v6 offset:1280
	ds_read_b64_tr_b16 v[36:37], v6 offset:224
	ds_read_b64_tr_b16 v[38:39], v6 offset:1312
	s_waitcnt lgkmcnt(14)
	v_mfma_f32_16x16x32_bf16 v[8:11], v[8:11], v[0:3], 0
	v_lshl_or_b32 v4, v4, 11, v5
	v_ashrrev_i32_e32 v5, 31, v4
	v_lshl_add_u64 v[4:5], v[4:5], 1, s[0:1]
	s_waitcnt lgkmcnt(12)
	v_mfma_f32_16x16x32_bf16 v[12:15], v[12:15], v[0:3], 0
	v_lshl_add_u64 v[4:5], v[4:5], 0, v[160:161]
	s_mov_b64 s[0:1], 0
	s_waitcnt lgkmcnt(10)
	v_mfma_f32_16x16x32_bf16 v[16:19], v[16:19], v[0:3], 0
	s_waitcnt lgkmcnt(8)
	v_mfma_f32_16x16x32_bf16 v[20:23], v[20:23], v[0:3], 0
	s_waitcnt lgkmcnt(6)
	v_mfma_f32_16x16x32_bf16 v[24:27], v[24:27], v[0:3], 0
	s_waitcnt lgkmcnt(4)
	v_mfma_f32_16x16x32_bf16 v[28:31], v[28:31], v[0:3], 0
	s_waitcnt lgkmcnt(2)
	v_mfma_f32_16x16x32_bf16 v[32:35], v[32:35], v[0:3], 0
	s_waitcnt lgkmcnt(0)
	v_mfma_f32_16x16x32_bf16 v[0:3], v[36:39], v[0:3], 0
	ds_read_b64_tr_b16 v[36:37], v7 offset:43520
	ds_read_b64_tr_b16 v[38:39], v7 offset:44608
	ds_read_b64_tr_b16 v[40:41], v6 offset:8704
	ds_read_b64_tr_b16 v[42:43], v6 offset:9792
	s_waitcnt lgkmcnt(0)
	v_mfma_f32_16x16x32_bf16 v[8:11], v[40:43], v[36:39], v[8:11]
	ds_read_b64_tr_b16 v[40:41], v6 offset:8736
	ds_read_b64_tr_b16 v[42:43], v6 offset:9824
	s_waitcnt lgkmcnt(0)
	v_mfma_f32_16x16x32_bf16 v[12:15], v[40:43], v[36:39], v[12:15]
	ds_read_b64_tr_b16 v[40:41], v6 offset:8768
	ds_read_b64_tr_b16 v[42:43], v6 offset:9856
	s_waitcnt lgkmcnt(0)
	v_mfma_f32_16x16x32_bf16 v[16:19], v[40:43], v[36:39], v[16:19]
	ds_read_b64_tr_b16 v[40:41], v6 offset:8800
	ds_read_b64_tr_b16 v[42:43], v6 offset:9888
	s_waitcnt lgkmcnt(0)
	v_mfma_f32_16x16x32_bf16 v[20:23], v[40:43], v[36:39], v[20:23]
	ds_read_b64_tr_b16 v[40:41], v6 offset:8832
	ds_read_b64_tr_b16 v[42:43], v6 offset:9920
	s_waitcnt lgkmcnt(0)
	v_mfma_f32_16x16x32_bf16 v[24:27], v[40:43], v[36:39], v[24:27]
	ds_read_b64_tr_b16 v[40:41], v6 offset:8864
	ds_read_b64_tr_b16 v[42:43], v6 offset:9952
	s_waitcnt lgkmcnt(0)
	v_mfma_f32_16x16x32_bf16 v[28:31], v[40:43], v[36:39], v[28:31]
	ds_read_b64_tr_b16 v[40:41], v6 offset:8896
	ds_read_b64_tr_b16 v[42:43], v6 offset:9984
	s_waitcnt lgkmcnt(0)
	v_mfma_f32_16x16x32_bf16 v[32:35], v[40:43], v[36:39], v[32:35]
	ds_read_b64_tr_b16 v[40:41], v6 offset:8928
	ds_read_b64_tr_b16 v[42:43], v6 offset:10016
	s_waitcnt lgkmcnt(0)
	v_mfma_f32_16x16x32_bf16 v[0:3], v[40:43], v[36:39], v[0:3]
	ds_read_b64_tr_b16 v[36:37], v7 offset:52224
	ds_read_b64_tr_b16 v[38:39], v7 offset:53312
	ds_read_b64_tr_b16 v[40:41], v6 offset:17408
	ds_read_b64_tr_b16 v[42:43], v6 offset:18496
	s_waitcnt lgkmcnt(0)
	v_mfma_f32_16x16x32_bf16 v[8:11], v[40:43], v[36:39], v[8:11]
	ds_read_b64_tr_b16 v[40:41], v6 offset:17440
	ds_read_b64_tr_b16 v[42:43], v6 offset:18528
	s_waitcnt lgkmcnt(0)
; DI unsigned pk2(float lo, float hi) { unsigned r; asm volatile("v_cvt_pk_bf16_f32 %0, %1, %2" : "=v"(r) : "v"(lo), "v"(hi)); return r; }
; DI f32x4 mmaT(bf16x8 a_m, bf16x8 b_n, f32x4 c) { return __builtin_amdgcn_mfma_f32_16x16x32_bf16(b_n, a_m, c, 0, 0, 0); }
; DI void ret_local_unit(const Params& p, int hf, int bl, int c, int hd, unsigned char* shm, int tid) {
;     ...
; #pragma unroll
;   for (int ks = 0; ks < 4; ++ks) {
;     const bf16x8 a = frag_tr(sV, LD, 32 * ks, 16 * wid, fr, fq);
; #pragma unroll
;     for (int n = 0; n < 8; ++n) acc[n] = mmaT(a, frag_tr(sK, LD, 32 * ks, 16 * n, fr, fq), acc[n]);
;   }
;   bf16_t* st = (bf16_t*)(wsb + WS_RST) + (size_t)((bl * 64 + c) * 4 + hd) * 16384;
; #pragma unroll
;   for (int n = 0; n < 8; ++n) { uint2 w; w.x = pk2(acc[n][0], acc[n][1]); w.y = pk2(acc[n][2], acc[n][3]); *(uint2*)(st + (16 * wid + fr) * 128 + 16 * n + 4 * fq) = w; }
;   __syncthreads();
	v_mfma_f32_16x16x32_bf16 v[12:15], v[40:43], v[36:39], v[12:15]
	ds_read_b64_tr_b16 v[40:41], v6 offset:17472
	ds_read_b64_tr_b16 v[42:43], v6 offset:18560
	s_waitcnt lgkmcnt(0)
	v_mfma_f32_16x16x32_bf16 v[16:19], v[40:43], v[36:39], v[16:19]
	ds_read_b64_tr_b16 v[40:41], v6 offset:17504
	ds_read_b64_tr_b16 v[42:43], v6 offset:18592
	s_waitcnt lgkmcnt(0)
	v_mfma_f32_16x16x32_bf16 v[20:23], v[40:43], v[36:39], v[20:23]
	ds_read_b64_tr_b16 v[40:41], v6 offset:17536
	ds_read_b64_tr_b16 v[42:43], v6 offset:18624
	s_waitcnt lgkmcnt(0)
	v_mfma_f32_16x16x32_bf16 v[24:27], v[40:43], v[36:39], v[24:27]
	ds_read_b64_tr_b16 v[40:41], v6 offset:17568
	ds_read_b64_tr_b16 v[42:43], v6 offset:18656
	s_waitcnt lgkmcnt(0)
	v_mfma_f32_16x16x32_bf16 v[28:31], v[40:43], v[36:39], v[28:31]
	ds_read_b64_tr_b16 v[40:41], v6 offset:17600
	ds_read_b64_tr_b16 v[42:43], v6 offset:18688
	s_waitcnt lgkmcnt(0)
	v_mfma_f32_16x16x32_bf16 v[32:35], v[40:43], v[36:39], v[32:35]
	ds_read_b64_tr_b16 v[40:41], v6 offset:17632
	ds_read_b64_tr_b16 v[42:43], v6 offset:18720
	s_waitcnt lgkmcnt(0)
	v_mfma_f32_16x16x32_bf16 v[0:3], v[40:43], v[36:39], v[0:3]
	ds_read_b64_tr_b16 v[36:37], v7 offset:60928
	ds_read_b64_tr_b16 v[38:39], v7 offset:62016
	ds_read_b64_tr_b16 v[40:41], v6 offset:26112
	ds_read_b64_tr_b16 v[42:43], v6 offset:27200
	s_waitcnt lgkmcnt(0)
	v_mfma_f32_16x16x32_bf16 v[8:11], v[40:43], v[36:39], v[8:11]
	ds_read_b64_tr_b16 v[40:41], v6 offset:26144
	ds_read_b64_tr_b16 v[42:43], v6 offset:27232
	s_waitcnt lgkmcnt(0)
	v_mfma_f32_16x16x32_bf16 v[12:15], v[40:43], v[36:39], v[12:15]
	ds_read_b64_tr_b16 v[40:41], v6 offset:26176
	ds_read_b64_tr_b16 v[42:43], v6 offset:27264
	s_waitcnt lgkmcnt(0)
	v_mfma_f32_16x16x32_bf16 v[16:19], v[40:43], v[36:39], v[16:19]
	ds_read_b64_tr_b16 v[40:41], v6 offset:26208
	ds_read_b64_tr_b16 v[42:43], v6 offset:27296
	s_waitcnt lgkmcnt(0)
	v_mfma_f32_16x16x32_bf16 v[20:23], v[40:43], v[36:39], v[20:23]
	ds_read_b64_tr_b16 v[40:41], v6 offset:26240
	ds_read_b64_tr_b16 v[42:43], v6 offset:27328
	s_waitcnt lgkmcnt(0)
	v_mfma_f32_16x16x32_bf16 v[24:27], v[40:43], v[36:39], v[24:27]
	ds_read_b64_tr_b16 v[40:41], v6 offset:26272
	ds_read_b64_tr_b16 v[42:43], v6 offset:27360
	s_waitcnt lgkmcnt(0)
	v_mfma_f32_16x16x32_bf16 v[28:31], v[40:43], v[36:39], v[28:31]
	ds_read_b64_tr_b16 v[40:41], v6 offset:26304
	ds_read_b64_tr_b16 v[42:43], v6 offset:27392
	s_waitcnt lgkmcnt(0)
	v_mfma_f32_16x16x32_bf16 v[32:35], v[40:43], v[36:39], v[32:35]
	ds_read_b64_tr_b16 v[40:41], v6 offset:26336
	ds_read_b64_tr_b16 v[42:43], v6 offset:27424
	v_cvt_pk_bf16_f32 v6, v8, v9
	v_cvt_pk_bf16_f32 v7, v10, v11
	global_store_dwordx2 v[4:5], v[6:7], off
	v_cvt_pk_bf16_f32 v6, v12, v13
	v_cvt_pk_bf16_f32 v7, v14, v15
	global_store_dwordx2 v[4:5], v[6:7], off offset:32
	v_cvt_pk_bf16_f32 v6, v16, v17
	v_cvt_pk_bf16_f32 v7, v18, v19
	global_store_dwordx2 v[4:5], v[6:7], off offset:64
	v_cvt_pk_bf16_f32 v6, v20, v21
	v_cvt_pk_bf16_f32 v7, v22, v23
	global_store_dwordx2 v[4:5], v[6:7], off offset:96
	v_cvt_pk_bf16_f32 v6, v24, v25
	v_cvt_pk_bf16_f32 v7, v26, v27
	s_waitcnt lgkmcnt(0)
	v_mfma_f32_16x16x32_bf16 v[0:3], v[40:43], v[36:39], v[0:3]
	global_store_dwordx2 v[4:5], v[6:7], off offset:128
	v_cvt_pk_bf16_f32 v6, v28, v29
	v_cvt_pk_bf16_f32 v7, v30, v31
	global_store_dwordx2 v[4:5], v[6:7], off offset:160
	v_cvt_pk_bf16_f32 v6, v32, v33
	v_cvt_pk_bf16_f32 v7, v34, v35
	global_store_dwordx2 v[4:5], v[6:7], off offset:192
	v_cvt_pk_bf16_f32 v0, v0, v1
	v_cvt_pk_bf16_f32 v1, v2, v3
	s_nop 4
	global_store_dwordx2 v[4:5], v[0:1], off offset:224
	s_barrier

; DI void norm_unit(const Params& p, int layer, int half, int nu, int tid) { norm_rows(p, layer, half * HROWS + nu * 64, 64, 0, 8, tid); }
; #define otid() otid_(wbase)
; __global__ void __launch_bounds__(NTHR) mega(Params p) {
;     ...
;         for (;;) {
;           __syncthreads();
;           if (otid() == 0) s_unit = atomicAdd(my, 1);
;           __syncthreads();
;           const int u0 = s_unit;
;           const int n_fill = (hf == 1) ? 256 : 0;
;           int u = u0;
;           if (u >= 1344 + n_fill) break;
;           if (u >= 448 && u < 448 + n_fill) { norm_unit(p, layer + 1, 0, u - 448, otid()); continue; }
;           if (u >= 448) u -= n_fill;
;           const bool needs = (u >= 448 && u < 576) || (u >= 832);
;           if (needs && !dep_ok) {
;             if (otid() == 0) {
;               unsigned sp = 0;
;               while (__hip_atomic_load(dep, __ATOMIC_RELAXED, __HIP_MEMORY_SCOPE_AGENT) < 192) { __builtin_amdgcn_s_sleep(2); if (++sp > (1u << 22)) break; }
.LBB0_413:
	v_mov_b32_e32 v0, v163
	s_nop 0
	v_cmp_eq_u32_e32 vcc, 0, v0
	s_and_saveexec_b64 s[0:1], vcc
	s_cbranch_execz .Lp4c_nb
	s_mov_b64 s[6:7], exec
	v_mbcnt_lo_u32_b32 v0, s6, 0
	v_mbcnt_hi_u32_b32 v0, s7, v0
	v_cmp_eq_u32_e32 vcc, 0, v0
	s_and_saveexec_b64 s[4:5], vcc
	s_cbranch_execz .LBB0_416
	s_bcnt1_i32_b64 s2, s[6:7]
	v_readlane_b32 s6, v254, 45
	v_mov_b32_e32 v1, s2
	v_readlane_b32 s7, v254, 46
	s_nop 4
	global_atomic_add v1, v161, v1, s[6:7] sc0
.LBB0_416:
	s_or_b64 exec, exec, s[4:5]
	s_barrier
	s_waitcnt vmcnt(0)
	v_readfirstlane_b32 s2, v1
	v_readlane_b32 s6, v254, 55
	v_readlane_b32 s7, v254, 56
	v_add_u32_e32 v0, s2, v0
	ds_write_b32 v161, v0 offset:16
	s_branch .LBB0_417
.Lp4c_nb:
	s_barrier
.LBB0_417:
	s_or_b64 exec, exec, s[0:1]
	s_waitcnt lgkmcnt(0)
	s_barrier
	ds_read_b32 v0, v161 offset:16
	v_readlane_b32 s0, v254, 47
	s_waitcnt lgkmcnt(0)
	v_readfirstlane_b32 s23, v0
	v_cmp_le_i32_e64 s[0:1], s0, v0
	s_and_b64 vcc, exec, s[0:1]
	s_cbranch_vccnz .LBB0_412
	v_writelane_b32 v254, s0, 57
	s_cmpk_gt_i32 s23, 0x1bf
	s_nop 0
	v_writelane_b32 v254, s1, 58
	s_cselect_b64 s[0:1], -1, 0
	v_readlane_b32 s2, v254, 48
	s_cmp_lt_i32 s23, s2
	s_cselect_b64 s[4:5], -1, 0
	s_and_b64 s[4:5], s[0:1], s[4:5]
	s_andn2_b64 vcc, exec, s[4:5]
	s_mov_b64 s[4:5], -1
	s_cbranch_vccz .LBB0_622
	s_and_b64 s[0:1], s[0:1], exec
	v_readlane_b32 s0, v254, 25
	s_cselect_b32 s0, s0, 0
	s_nop 0
	v_writelane_b32 v254, s0, 59
	s_mov_b32 s100, 0xffffff40
	s_cmp_lt_u32 s23, 0xc0
	s_cselect_b32 s100, 0x100, s100
	s_cmp_lt_u32 s23, 0x1c0
	s_cselect_b32 s100, s100, 0
	s_add_i32 s23, s23, s100
	s_sub_i32 s0, s23, s0
	s_add_i32 s16, s0, 0xfffffe40
	v_writelane_b32 v254, s0, 60
	s_cmpk_lt_i32 s0, 0x340
	v_readlane_b32 s4, v254, 53
	s_cselect_b64 s[0:1], -1, 0
	v_readlane_b32 s5, v254, 54
	s_or_b64 s[0:1], s[0:1], s[4:5]
	s_cmpk_lt_u32 s16, 0x80
	v_cndmask_b32_e64 v0, 0, 1, s[0:1]
	v_cndmask_b32_e64 v1, 0, 1, s[4:5]
	s_cselect_b64 vcc, -1, 0
	v_cndmask_b32_e32 v0, v0, v1, vcc
	v_and_b32_e32 v0, 1, v0
	v_cmp_eq_u32_e32 vcc, 1, v0
	s_cbranch_vccnz .LBB0_431
	v_mov_b32_e32 v0, v163
	s_nop 0
	v_cmp_eq_u32_e32 vcc, 0, v0
	s_and_saveexec_b64 s[0:1], vcc
	s_cbranch_execz .LBB0_430
	s_mov_b32 s2, 0x400001
	s_branch .LBB0_423
